# G2 in groups of 4 tokens x two half-list sweeps (partials in LDS), G1 writes expert list partitioned by table half for L2 locality
# speedup vs baseline: 1.0192x; 1.0192x over previous
.LBB0_995:
	v_add_u32_e32 v68, s28, v132
	ds_read_b128 v[40:43], v68
	ds_read_b128 v[44:47], v68 offset:256
	ds_read_b128 v[48:51], v68 offset:512
	ds_read_b128 v[52:55], v68 offset:768
	ds_read_b128 v[56:59], v68 offset:1024
	ds_read_b128 v[60:63], v68 offset:1280
	ds_read_b128 v[64:67], v68 offset:1536
	ds_read_b128 v[68:71], v68 offset:1792
	s_waitcnt lgkmcnt(7)
	v_cmp_gt_u32_e32 vcc, v40, v29
	s_waitcnt lgkmcnt(6)
	v_cmp_gt_u32_e64 s[14:15], v46, v30
	s_waitcnt lgkmcnt(5)
	v_cmp_gt_u32_e64 s[16:17], v50, v31
	v_cndmask_b32_e64 v40, 0, 1, vcc
	v_cmp_gt_u32_e32 vcc, v42, v29
	s_waitcnt lgkmcnt(4)
	v_cmp_gt_u32_e64 s[18:19], v54, v33
	s_waitcnt lgkmcnt(3)
	v_cmp_gt_u32_e64 s[20:21], v58, v34
	v_cndmask_b32_e64 v42, 0, 1, vcc
	v_cmp_gt_u32_e32 vcc, v44, v30
	s_waitcnt lgkmcnt(2)
	v_cmp_gt_u32_e64 s[22:23], v62, v36
	s_waitcnt lgkmcnt(1)
	v_cmp_gt_u32_e64 s[24:25], v66, v37
	v_cndmask_b32_e64 v44, 0, 1, vcc
	v_cmp_gt_u32_e32 vcc, v45, v30
	v_cndmask_b32_e64 v45, 0, 1, s[14:15]
	v_cmp_gt_u32_e64 s[14:15], v48, v31
	v_cndmask_b32_e64 v48, 0, 1, s[16:17]
	v_cmp_gt_u32_e64 s[16:17], v52, v33
	v_cndmask_b32_e64 v46, 0, 1, s[14:15]
	v_cmp_gt_u32_e64 s[14:15], v49, v31
	v_cndmask_b32_e64 v49, 0, 1, s[16:17]
	v_cmp_gt_u32_e64 s[16:17], v53, v33
	v_cndmask_b32_e64 v50, 0, 1, s[18:19]
	v_cmp_gt_u32_e64 s[18:19], v56, v34
	v_cndmask_b32_e64 v53, 0, 1, s[20:21]
	v_cmp_gt_u32_e64 s[20:21], v60, v36
	v_cndmask_b32_e64 v56, 0, 1, s[22:23]
	v_cmp_gt_u32_e64 s[22:23], v64, v37
	v_cndmask_b32_e64 v58, 0, 1, s[24:25]
	s_waitcnt lgkmcnt(0)
	v_cmp_gt_u32_e64 s[24:25], v68, v39
	v_cmp_gt_u32_e64 s[26:27], v70, v39
	v_cndmask_b32_e64 v52, 0, 1, s[18:19]
	v_cmp_gt_u32_e64 s[18:19], v57, v34
	v_cndmask_b32_e64 v54, 0, 1, s[20:21]
	v_cmp_gt_u32_e64 s[20:21], v61, v36
	v_cndmask_b32_e64 v57, 0, 1, s[22:23]
	v_cmp_gt_u32_e64 s[22:23], v65, v37
	v_cndmask_b32_e64 v60, 0, 1, s[24:25]
	v_cmp_gt_u32_e64 s[24:25], v69, v39
	v_cndmask_b32_e64 v61, 0, 1, s[26:27]
	v_cmp_gt_u32_e64 s[26:27], v41, v29
	v_addc_co_u32_e32 v35, vcc, v35, v44, vcc
	s_nop 0
	v_addc_co_u32_e64 v38, s[26:27], v38, v40, s[26:27]
	v_addc_co_u32_e64 v32, s[14:15], v32, v46, s[14:15]
	v_addc_co_u32_e64 v28, s[16:17], v28, v49, s[16:17]
	v_addc_co_u32_e64 v24, s[18:19], v24, v52, s[18:19]
	v_addc_co_u32_e64 v19, s[20:21], v19, v54, s[20:21]
	v_addc_co_u32_e64 v12, s[22:23], v12, v57, s[22:23]
	v_addc_co_u32_e64 v5, s[24:25], v5, v60, s[24:25]
	s_add_i32 s28, s28, 16
	v_cmp_gt_u32_e32 vcc, v47, v30
	v_cmp_gt_u32_e64 s[14:15], v51, v31
	v_cmp_gt_u32_e64 s[16:17], v55, v33
	v_cmp_gt_u32_e64 s[18:19], v59, v34
	v_cmp_gt_u32_e64 s[20:21], v63, v36
	v_cmp_gt_u32_e64 s[22:23], v67, v37
	v_cmp_gt_u32_e64 s[24:25], v71, v39
	v_cmp_gt_u32_e64 s[26:27], v43, v29
	s_cmpk_eq_i32 s28, 0xd0
	v_addc_co_u32_e32 v35, vcc, v35, v45, vcc
	v_addc_co_u32_e64 v38, s[26:27], v38, v42, s[26:27]
	v_addc_co_u32_e64 v32, vcc, v32, v48, s[14:15]
	v_addc_co_u32_e64 v28, vcc, v28, v50, s[16:17]
	v_addc_co_u32_e64 v24, vcc, v24, v53, s[18:19]
	v_addc_co_u32_e64 v19, vcc, v19, v56, s[20:21]
	v_addc_co_u32_e64 v12, vcc, v12, v58, s[22:23]
	v_addc_co_u32_e64 v5, vcc, v5, v61, s[24:25]
	s_cbranch_scc0 .LBB0_995
	s_mov_b32 s77, 0
	s_movk_i32 s78, 0x7f
	v_readfirstlane_b32 s14, v27
	v_cmp_gt_i32_e32 vcc, 16, v38
	v_mov_b32_e32 v143, 0
	v_subrev_f32_e32 v27, s14, v27
	v_mul_f32_e32 v27, 0x3fb8aa3b, v27
	v_exp_f32_e32 v27, v27
	s_and_b64 s[14:15], s[4:5], vcc
	v_lshl_add_u32 v142, v38, 2, v127
	v_and_b32_e32 v184, 64, v25
	v_cmp_eq_u32_e32 vcc, 0, v184
	s_and_b64 s[72:73], vcc, s[14:15]
	s_andn2_b64 s[74:75], s[14:15], vcc
	v_mbcnt_lo_u32_b32 v184, s72, 0
	v_mbcnt_hi_u32_b32 v184, s73, v184
	v_mbcnt_lo_u32_b32 v185, s74, 0
	v_mbcnt_hi_u32_b32 v185, s75, v185
	v_add_u32_e32 v184, s77, v184
	v_sub_u32_e32 v185, s78, v185
	v_cndmask_b32_e32 v184, v185, v184, vcc
	v_lshl_add_u32 v142, v184, 2, v127
	s_bcnt1_i32_b64 s76, s[72:73]
	s_add_u32 s77, s77, s76
	s_bcnt1_i32_b64 s76, s[74:75]
	s_sub_u32 s78, s78, s76
	v_mov_b32_e32 v144, 0
	v_cndmask_b32_e64 v29, 0, v27, s[14:15]
	v_mov_b32_e32 v30, v29
	s_nop 1
	v_permlane32_swap_b32_e32 v29, v30
	v_add_f32_e32 v29, v29, v30
	v_mov_b32_e32 v30, v29
	s_nop 1
	v_permlane16_swap_b32_e32 v29, v30
	v_add_f32_e32 v29, v29, v30
	v_mov_b32_e32 v145, 0
	s_nop 0
	v_add_f32_dpp v29, v29, v29 row_ror:8 row_mask:0xf bank_mask:0xf bound_ctrl:1
	s_nop 1
	v_add_f32_dpp v29, v29, v29 row_ror:4 row_mask:0xf bank_mask:0xf bound_ctrl:1
	s_nop 1
	v_add_f32_dpp v29, v29, v29 quad_perm:[2,3,0,1] row_mask:0xf bank_mask:0xf bound_ctrl:1
	s_nop 1
	v_mov_b32_dpp v30, v29 quad_perm:[1,0,3,2] row_mask:0xf bank_mask:0xf bound_ctrl:1
	s_and_saveexec_b64 s[16:17], s[14:15]
	s_cbranch_execz .LBB0_998
	v_lshlrev_b32_e32 v25, 7, v25
	v_and_b32_e32 v26, 0x7f, v26
	v_and_or_b32 v25, v25, s49, v26
	v_lshlrev_b32_e32 v26, 2, v25
	global_load_dword v145, v26, s[36:37]
	global_load_dword v144, v26, s[38:39]
	v_add_f32_e32 v26, v29, v30
	v_div_scale_f32 v29, s[18:19], v26, v26, v27
	v_rcp_f32_e32 v30, v29
	s_nop 0
	v_fma_f32 v31, -v29, v30, 1.0
	v_fmac_f32_e32 v30, v31, v30
	v_div_scale_f32 v31, vcc, v27, v26, v27
	v_mul_f32_e32 v33, v31, v30
	v_fma_f32 v34, -v29, v33, v31
	v_fmac_f32_e32 v33, v34, v30
	v_fma_f32 v29, -v29, v33, v31
	v_div_fmas_f32 v29, v29, v30, v33
	v_div_fixup_f32 v26, v29, v26, v27
	ds_write2st64_b32 v142, v25, v26 offset0:12 offset1:14
.LBB0_998:
	s_or_b64 exec, exec, s[16:17]
	v_readfirstlane_b32 s16, v23
	v_cmp_gt_i32_e32 vcc, 16, v35
	v_lshl_add_u32 v27, v35, 2, v127
	v_subrev_f32_e32 v23, s16, v23
	v_mul_f32_e32 v23, 0x3fb8aa3b, v23
	v_exp_f32_e32 v23, v23
	s_and_b64 s[16:17], s[4:5], vcc
	v_add_u32_e32 v146, 64, v27
	v_and_b32_e32 v184, 64, v20
	v_cmp_eq_u32_e32 vcc, 0, v184
	s_and_b64 s[72:73], vcc, s[16:17]
	s_andn2_b64 s[74:75], s[16:17], vcc
	v_mbcnt_lo_u32_b32 v184, s72, 0
	v_mbcnt_hi_u32_b32 v184, s73, v184
	v_mbcnt_lo_u32_b32 v185, s74, 0
	v_mbcnt_hi_u32_b32 v185, s75, v185
	v_add_u32_e32 v184, s77, v184
	v_sub_u32_e32 v185, s78, v185
	v_cndmask_b32_e32 v184, v185, v184, vcc
	v_lshl_add_u32 v146, v184, 2, v127
	s_bcnt1_i32_b64 s76, s[72:73]
	s_add_u32 s77, s77, s76
	s_bcnt1_i32_b64 s76, s[74:75]
	s_sub_u32 s78, s78, s76
	v_mov_b32_e32 v147, 0
	v_cndmask_b32_e64 v25, 0, v23, s[16:17]
	v_mov_b32_e32 v26, v25
	s_nop 1
	v_permlane32_swap_b32_e32 v25, v26
	v_add_f32_e32 v25, v25, v26
	v_mov_b32_e32 v26, v25
	s_nop 1
	v_permlane16_swap_b32_e32 v25, v26
	v_add_f32_e32 v25, v25, v26
	s_nop 1
	v_add_f32_dpp v25, v25, v25 row_ror:8 row_mask:0xf bank_mask:0xf bound_ctrl:1
	s_nop 1
	v_add_f32_dpp v25, v25, v25 row_ror:4 row_mask:0xf bank_mask:0xf bound_ctrl:1
	s_nop 1
	v_add_f32_dpp v25, v25, v25 quad_perm:[2,3,0,1] row_mask:0xf bank_mask:0xf bound_ctrl:1
	s_nop 1
	v_mov_b32_dpp v26, v25 quad_perm:[1,0,3,2] row_mask:0xf bank_mask:0xf bound_ctrl:1
	s_and_saveexec_b64 s[18:19], s[16:17]
	s_cbranch_execz .LBB0_1000
	v_lshlrev_b32_e32 v20, 7, v20
	v_and_b32_e32 v21, 0x7f, v21
	v_and_or_b32 v20, v20, s49, v21
	v_lshlrev_b32_e32 v21, 2, v20
	global_load_dword v147, v21, s[36:37]
	global_load_dword v143, v21, s[38:39]
	v_add_f32_e32 v21, v25, v26
	v_div_scale_f32 v25, s[20:21], v21, v21, v23
	v_rcp_f32_e32 v26, v25
	s_nop 0
	v_fma_f32 v27, -v25, v26, 1.0
	v_fmac_f32_e32 v26, v27, v26
	v_div_scale_f32 v27, vcc, v23, v21, v23
	v_mul_f32_e32 v29, v27, v26
	v_fma_f32 v30, -v25, v29, v27
	v_fmac_f32_e32 v29, v30, v26
	v_fma_f32 v25, -v25, v29, v27
	v_div_fmas_f32 v25, v25, v26, v29
	v_div_fixup_f32 v21, v25, v21, v23
	ds_write2st64_b32 v146, v20, v21 offset0:12 offset1:14
.LBB0_1000:
	s_or_b64 exec, exec, s[18:19]
	v_readfirstlane_b32 s18, v22
	v_cmp_gt_i32_e32 vcc, 16, v32
	v_lshl_add_u32 v23, v32, 2, v127
	v_subrev_f32_e32 v20, s18, v22
	v_mul_f32_e32 v20, 0x3fb8aa3b, v20
	v_exp_f32_e32 v20, v20
	s_and_b64 s[18:19], s[4:5], vcc
	v_mov_b32_e32 v149, 0
	v_add_u32_e32 v148, 0x80, v23
	v_and_b32_e32 v184, 64, v17
	v_cmp_eq_u32_e32 vcc, 0, v184
	s_and_b64 s[72:73], vcc, s[18:19]
	s_andn2_b64 s[74:75], s[18:19], vcc
	v_mbcnt_lo_u32_b32 v184, s72, 0
	v_mbcnt_hi_u32_b32 v184, s73, v184
	v_mbcnt_lo_u32_b32 v185, s74, 0
	v_mbcnt_hi_u32_b32 v185, s75, v185
	v_add_u32_e32 v184, s77, v184
	v_sub_u32_e32 v185, s78, v185
	v_cndmask_b32_e32 v184, v185, v184, vcc
	v_lshl_add_u32 v148, v184, 2, v127
	s_bcnt1_i32_b64 s76, s[72:73]
	s_add_u32 s77, s77, s76
	s_bcnt1_i32_b64 s76, s[74:75]
	s_sub_u32 s78, s78, s76
	v_cndmask_b32_e64 v21, 0, v20, s[18:19]
	v_mov_b32_e32 v22, v21
	s_nop 1
	v_permlane32_swap_b32_e32 v21, v22
	v_add_f32_e32 v21, v21, v22
	v_mov_b32_e32 v22, v21
	s_nop 1
	v_permlane16_swap_b32_e32 v21, v22
	v_add_f32_e32 v21, v21, v22
	v_mov_b32_e32 v150, 0
	v_mov_b32_e32 v151, 0
	v_add_f32_dpp v21, v21, v21 row_ror:8 row_mask:0xf bank_mask:0xf bound_ctrl:1
	s_nop 1
	v_add_f32_dpp v21, v21, v21 row_ror:4 row_mask:0xf bank_mask:0xf bound_ctrl:1
	s_nop 1
	v_add_f32_dpp v21, v21, v21 quad_perm:[2,3,0,1] row_mask:0xf bank_mask:0xf bound_ctrl:1
	s_nop 1
	v_mov_b32_dpp v22, v21 quad_perm:[1,0,3,2] row_mask:0xf bank_mask:0xf bound_ctrl:1
	s_and_saveexec_b64 s[20:21], s[18:19]
	s_cbranch_execz .LBB0_1002
	v_lshlrev_b32_e32 v17, 7, v17
	v_and_b32_e32 v18, 0x7f, v18
	v_and_or_b32 v17, v17, s49, v18
	v_lshlrev_b32_e32 v18, 2, v17
	global_load_dword v151, v18, s[36:37]
	global_load_dword v150, v18, s[38:39]
	v_add_f32_e32 v18, v21, v22
	v_div_scale_f32 v21, s[22:23], v18, v18, v20
	v_rcp_f32_e32 v22, v21
	s_nop 0
	v_fma_f32 v23, -v21, v22, 1.0
	v_fmac_f32_e32 v22, v23, v22
	v_div_scale_f32 v23, vcc, v20, v18, v20
	v_mul_f32_e32 v25, v23, v22
	v_fma_f32 v26, -v21, v25, v23
	v_fmac_f32_e32 v25, v26, v22
	v_fma_f32 v21, -v21, v25, v23
	v_div_fmas_f32 v21, v21, v22, v25
	v_div_fixup_f32 v18, v21, v18, v20
	ds_write2st64_b32 v148, v17, v18 offset0:12 offset1:14
.LBB0_1002:
	s_or_b64 exec, exec, s[20:21]
	v_readfirstlane_b32 s20, v16
	v_cmp_gt_i32_e32 vcc, 16, v28
	v_lshl_add_u32 v20, v28, 2, v127
	v_subrev_f32_e32 v16, s20, v16
	v_mul_f32_e32 v16, 0x3fb8aa3b, v16
	v_exp_f32_e32 v16, v16
	s_and_b64 s[20:21], s[4:5], vcc
	v_add_u32_e32 v152, 0xc0, v20
	v_and_b32_e32 v184, 64, v13
	v_cmp_eq_u32_e32 vcc, 0, v184
	s_and_b64 s[72:73], vcc, s[20:21]
	s_andn2_b64 s[74:75], s[20:21], vcc
	v_mbcnt_lo_u32_b32 v184, s72, 0
	v_mbcnt_hi_u32_b32 v184, s73, v184
	v_mbcnt_lo_u32_b32 v185, s74, 0
	v_mbcnt_hi_u32_b32 v185, s75, v185
	v_add_u32_e32 v184, s77, v184
	v_sub_u32_e32 v185, s78, v185
	v_cndmask_b32_e32 v184, v185, v184, vcc
	v_lshl_add_u32 v152, v184, 2, v127
	s_bcnt1_i32_b64 s76, s[72:73]
	s_add_u32 s77, s77, s76
	s_bcnt1_i32_b64 s76, s[74:75]
	s_sub_u32 s78, s78, s76
	v_mov_b32_e32 v153, 0
	v_cndmask_b32_e64 v17, 0, v16, s[20:21]
	v_mov_b32_e32 v18, v17
	s_nop 1
	v_permlane32_swap_b32_e32 v17, v18
	v_add_f32_e32 v17, v17, v18
	v_mov_b32_e32 v18, v17
	s_nop 1
	v_permlane16_swap_b32_e32 v17, v18
	v_add_f32_e32 v17, v17, v18
	s_nop 1
	v_add_f32_dpp v17, v17, v17 row_ror:8 row_mask:0xf bank_mask:0xf bound_ctrl:1
	s_nop 1
	v_add_f32_dpp v17, v17, v17 row_ror:4 row_mask:0xf bank_mask:0xf bound_ctrl:1
	s_nop 1
	v_add_f32_dpp v17, v17, v17 quad_perm:[2,3,0,1] row_mask:0xf bank_mask:0xf bound_ctrl:1
	s_nop 1
	v_mov_b32_dpp v18, v17 quad_perm:[1,0,3,2] row_mask:0xf bank_mask:0xf bound_ctrl:1
	s_and_saveexec_b64 s[22:23], s[20:21]
	s_cbranch_execz .LBB0_1004
	v_lshlrev_b32_e32 v13, 7, v13
	v_and_b32_e32 v14, 0x7f, v14
	v_and_or_b32 v13, v13, s49, v14
	v_lshlrev_b32_e32 v14, 2, v13
	global_load_dword v153, v14, s[36:37]
	global_load_dword v149, v14, s[38:39]
	v_add_f32_e32 v14, v17, v18
	v_div_scale_f32 v17, s[24:25], v14, v14, v16
	v_rcp_f32_e32 v18, v17
	s_nop 0
	v_fma_f32 v20, -v17, v18, 1.0
	v_fmac_f32_e32 v18, v20, v18
	v_div_scale_f32 v20, vcc, v16, v14, v16
	v_mul_f32_e32 v21, v20, v18
	v_fma_f32 v22, -v17, v21, v20
	v_fmac_f32_e32 v21, v22, v18
	v_fma_f32 v17, -v17, v21, v20
	v_div_fmas_f32 v17, v17, v18, v21
	v_div_fixup_f32 v14, v17, v14, v16
	ds_write2st64_b32 v152, v13, v14 offset0:12 offset1:14
.LBB0_1004:
	s_or_b64 exec, exec, s[22:23]
	v_readfirstlane_b32 s22, v15
	v_cmp_gt_i32_e32 vcc, 16, v24
	v_mov_b32_e32 v155, 0
	v_subrev_f32_e32 v13, s22, v15
	v_mul_f32_e32 v13, 0x3fb8aa3b, v13
	v_exp_f32_e32 v13, v13
	s_and_b64 s[22:23], s[4:5], vcc
	v_lshl_add_u32 v154, v24, 2, v127
	v_and_b32_e32 v184, 64, v10
	v_cmp_eq_u32_e32 vcc, 0, v184
	s_and_b64 s[72:73], vcc, s[22:23]
	s_andn2_b64 s[74:75], s[22:23], vcc
	v_mbcnt_lo_u32_b32 v184, s72, 0
	v_mbcnt_hi_u32_b32 v184, s73, v184
	v_mbcnt_lo_u32_b32 v185, s74, 0
	v_mbcnt_hi_u32_b32 v185, s75, v185
	v_add_u32_e32 v184, s77, v184
	v_sub_u32_e32 v185, s78, v185
	v_cndmask_b32_e32 v184, v185, v184, vcc
	v_lshl_add_u32 v154, v184, 2, v127
	s_bcnt1_i32_b64 s76, s[72:73]
	s_add_u32 s77, s77, s76
	s_bcnt1_i32_b64 s76, s[74:75]
	s_sub_u32 s78, s78, s76
	v_mov_b32_e32 v156, 0
	v_cndmask_b32_e64 v14, 0, v13, s[22:23]
	v_mov_b32_e32 v15, v14
	s_nop 1
	v_permlane32_swap_b32_e32 v14, v15
	v_add_f32_e32 v14, v14, v15
	v_mov_b32_e32 v15, v14
	s_nop 1
	v_permlane16_swap_b32_e32 v14, v15
	v_add_f32_e32 v14, v14, v15
	v_mov_b32_e32 v157, 0
	s_nop 0
	v_add_f32_dpp v14, v14, v14 row_ror:8 row_mask:0xf bank_mask:0xf bound_ctrl:1
	s_nop 1
	v_add_f32_dpp v14, v14, v14 row_ror:4 row_mask:0xf bank_mask:0xf bound_ctrl:1
	s_nop 1
	v_add_f32_dpp v14, v14, v14 quad_perm:[2,3,0,1] row_mask:0xf bank_mask:0xf bound_ctrl:1
	s_nop 1
	v_mov_b32_dpp v15, v14 quad_perm:[1,0,3,2] row_mask:0xf bank_mask:0xf bound_ctrl:1
	s_and_saveexec_b64 s[24:25], s[22:23]
	s_cbranch_execz .LBB0_1006
	v_lshlrev_b32_e32 v10, 7, v10
	v_and_b32_e32 v11, 0x7f, v11
	v_and_or_b32 v10, v10, s49, v11
	v_lshlrev_b32_e32 v11, 2, v10
	global_load_dword v157, v11, s[36:37]
	global_load_dword v156, v11, s[38:39]
	v_add_f32_e32 v11, v14, v15
	v_div_scale_f32 v14, s[26:27], v11, v11, v13
	v_rcp_f32_e32 v15, v14
	s_nop 0
	v_fma_f32 v16, -v14, v15, 1.0
	v_fmac_f32_e32 v15, v16, v15
	v_div_scale_f32 v16, vcc, v13, v11, v13
	v_mul_f32_e32 v17, v16, v15
	v_fma_f32 v18, -v14, v17, v16
	v_fmac_f32_e32 v17, v18, v15
	v_fma_f32 v14, -v14, v17, v16
	v_div_fmas_f32 v14, v14, v15, v17
	v_div_fixup_f32 v11, v14, v11, v13
	ds_write2st64_b32 v154, v10, v11 offset0:12 offset1:14
.LBB0_1006:
	s_or_b64 exec, exec, s[24:25]
	v_readfirstlane_b32 s24, v9
	v_cmp_gt_i32_e32 vcc, 16, v19
	v_lshl_add_u32 v13, v19, 2, v127
	v_subrev_f32_e32 v9, s24, v9
	v_mul_f32_e32 v9, 0x3fb8aa3b, v9
	v_exp_f32_e32 v9, v9
	s_and_b64 s[24:25], s[4:5], vcc
	v_add_u32_e32 v158, 64, v13
	v_and_b32_e32 v184, 64, v6
	v_cmp_eq_u32_e32 vcc, 0, v184
	s_and_b64 s[72:73], vcc, s[24:25]
	s_andn2_b64 s[74:75], s[24:25], vcc
	v_mbcnt_lo_u32_b32 v184, s72, 0
	v_mbcnt_hi_u32_b32 v184, s73, v184
	v_mbcnt_lo_u32_b32 v185, s74, 0
	v_mbcnt_hi_u32_b32 v185, s75, v185
	v_add_u32_e32 v184, s77, v184
	v_sub_u32_e32 v185, s78, v185
	v_cndmask_b32_e32 v184, v185, v184, vcc
	v_lshl_add_u32 v158, v184, 2, v127
	s_bcnt1_i32_b64 s76, s[72:73]
	s_add_u32 s77, s77, s76
	s_bcnt1_i32_b64 s76, s[74:75]
	s_sub_u32 s78, s78, s76
	v_mov_b32_e32 v159, 0
	v_cndmask_b32_e64 v10, 0, v9, s[24:25]
	v_mov_b32_e32 v11, v10
	s_nop 1
	v_permlane32_swap_b32_e32 v10, v11
	v_add_f32_e32 v10, v10, v11
	v_mov_b32_e32 v11, v10
	s_nop 1
	v_permlane16_swap_b32_e32 v10, v11
	v_add_f32_e32 v10, v10, v11
	s_nop 1
	v_add_f32_dpp v10, v10, v10 row_ror:8 row_mask:0xf bank_mask:0xf bound_ctrl:1
	s_nop 1
	v_add_f32_dpp v10, v10, v10 row_ror:4 row_mask:0xf bank_mask:0xf bound_ctrl:1
	s_nop 1
	v_add_f32_dpp v10, v10, v10 quad_perm:[2,3,0,1] row_mask:0xf bank_mask:0xf bound_ctrl:1
	s_nop 1
	v_mov_b32_dpp v11, v10 quad_perm:[1,0,3,2] row_mask:0xf bank_mask:0xf bound_ctrl:1
	s_and_saveexec_b64 s[26:27], s[24:25]
	s_cbranch_execz .LBB0_1008
	v_lshlrev_b32_e32 v6, 7, v6
	v_and_b32_e32 v7, 0x7f, v7
	v_and_or_b32 v6, v6, s49, v7
	v_lshlrev_b32_e32 v7, 2, v6
	global_load_dword v159, v7, s[36:37]
	global_load_dword v155, v7, s[38:39]
	v_add_f32_e32 v7, v10, v11
	v_div_scale_f32 v10, s[28:29], v7, v7, v9
	v_rcp_f32_e32 v11, v10
	s_nop 0
	v_fma_f32 v13, -v10, v11, 1.0
	v_fmac_f32_e32 v11, v13, v11
	v_div_scale_f32 v13, vcc, v9, v7, v9
	v_mul_f32_e32 v14, v13, v11
	v_fma_f32 v15, -v10, v14, v13
	v_fmac_f32_e32 v14, v15, v11
	v_fma_f32 v10, -v10, v14, v13
	v_div_fmas_f32 v10, v10, v11, v14
	v_div_fixup_f32 v7, v10, v7, v9
	ds_write2st64_b32 v158, v6, v7 offset0:12 offset1:14
.LBB0_1008:
	s_or_b64 exec, exec, s[26:27]
	v_readfirstlane_b32 s26, v8
	v_cmp_gt_i32_e32 vcc, 16, v12
	v_lshl_add_u32 v9, v12, 2, v127
	v_subrev_f32_e32 v6, s26, v8
	v_mul_f32_e32 v6, 0x3fb8aa3b, v6
	v_exp_f32_e32 v6, v6
	s_and_b64 s[26:27], s[4:5], vcc
	v_mov_b32_e32 v161, 0
	v_add_u32_e32 v160, 0x80, v9
	v_and_b32_e32 v184, 64, v3
	v_cmp_eq_u32_e32 vcc, 0, v184
	s_and_b64 s[72:73], vcc, s[26:27]
	s_andn2_b64 s[74:75], s[26:27], vcc
	v_mbcnt_lo_u32_b32 v184, s72, 0
	v_mbcnt_hi_u32_b32 v184, s73, v184
	v_mbcnt_lo_u32_b32 v185, s74, 0
	v_mbcnt_hi_u32_b32 v185, s75, v185
	v_add_u32_e32 v184, s77, v184
	v_sub_u32_e32 v185, s78, v185
	v_cndmask_b32_e32 v184, v185, v184, vcc
	v_lshl_add_u32 v160, v184, 2, v127
	s_bcnt1_i32_b64 s76, s[72:73]
	s_add_u32 s77, s77, s76
	s_bcnt1_i32_b64 s76, s[74:75]
	s_sub_u32 s78, s78, s76
	v_cndmask_b32_e64 v7, 0, v6, s[26:27]
	v_mov_b32_e32 v8, v7
	s_nop 1
	v_permlane32_swap_b32_e32 v7, v8
	v_add_f32_e32 v7, v7, v8
	v_mov_b32_e32 v8, v7
	s_nop 1
	v_permlane16_swap_b32_e32 v7, v8
	v_add_f32_e32 v7, v7, v8
	v_mov_b32_e32 v162, 0
	v_mov_b32_e32 v163, 0
	v_add_f32_dpp v7, v7, v7 row_ror:8 row_mask:0xf bank_mask:0xf bound_ctrl:1
	s_nop 1
	v_add_f32_dpp v7, v7, v7 row_ror:4 row_mask:0xf bank_mask:0xf bound_ctrl:1
	s_nop 1
	v_add_f32_dpp v7, v7, v7 quad_perm:[2,3,0,1] row_mask:0xf bank_mask:0xf bound_ctrl:1
	s_nop 1
	v_mov_b32_dpp v8, v7 quad_perm:[1,0,3,2] row_mask:0xf bank_mask:0xf bound_ctrl:1
	s_and_saveexec_b64 s[28:29], s[26:27]
	s_cbranch_execz .LBB0_1010
	v_lshlrev_b32_e32 v3, 7, v3
	v_and_b32_e32 v4, 0x7f, v4
	v_and_or_b32 v3, v3, s49, v4
	v_lshlrev_b32_e32 v4, 2, v3
	global_load_dword v163, v4, s[36:37]
	global_load_dword v162, v4, s[38:39]
	v_add_f32_e32 v4, v7, v8
	v_div_scale_f32 v7, s[42:43], v4, v4, v6
	v_rcp_f32_e32 v8, v7
	s_nop 0
	v_fma_f32 v9, -v7, v8, 1.0
	v_fmac_f32_e32 v8, v9, v8
	v_div_scale_f32 v9, vcc, v6, v4, v6
	v_mul_f32_e32 v10, v9, v8
	v_fma_f32 v11, -v7, v10, v9
	v_fmac_f32_e32 v10, v11, v8
	v_fma_f32 v7, -v7, v10, v9
	v_div_fmas_f32 v7, v7, v8, v10
	v_div_fixup_f32 v4, v7, v4, v6
	ds_write2st64_b32 v160, v3, v4 offset0:12 offset1:14
.LBB0_1010:
	s_or_b64 exec, exec, s[28:29]
	v_readfirstlane_b32 s28, v2
	v_cmp_gt_i32_e32 vcc, 16, v5
	v_lshl_add_u32 v5, v5, 2, v127
	v_subrev_f32_e32 v2, s28, v2
	v_mul_f32_e32 v2, 0x3fb8aa3b, v2
	v_exp_f32_e32 v2, v2
	s_and_b64 s[28:29], s[4:5], vcc
	v_add_u32_e32 v164, 0xc0, v5
	v_and_b32_e32 v184, 64, v0
	v_cmp_eq_u32_e32 vcc, 0, v184
	s_and_b64 s[72:73], vcc, s[28:29]
	s_andn2_b64 s[74:75], s[28:29], vcc
	v_mbcnt_lo_u32_b32 v184, s72, 0
	v_mbcnt_hi_u32_b32 v184, s73, v184
	v_mbcnt_lo_u32_b32 v185, s74, 0
	v_mbcnt_hi_u32_b32 v185, s75, v185
	v_add_u32_e32 v184, s77, v184
	v_sub_u32_e32 v185, s78, v185
	v_cndmask_b32_e32 v184, v185, v184, vcc
	v_lshl_add_u32 v164, v184, 2, v127
	s_bcnt1_i32_b64 s76, s[72:73]
	s_add_u32 s77, s77, s76
	s_bcnt1_i32_b64 s76, s[74:75]
	s_sub_u32 s78, s78, s76
	v_mov_b32_e32 v165, 0
	v_cndmask_b32_e64 v3, 0, v2, s[28:29]
	v_mov_b32_e32 v4, v3
	s_nop 1
	v_permlane32_swap_b32_e32 v3, v4
	v_add_f32_e32 v3, v3, v4
	v_mov_b32_e32 v4, v3
	s_nop 1
	v_permlane16_swap_b32_e32 v3, v4
	v_add_f32_e32 v3, v3, v4
	s_nop 1
	v_add_f32_dpp v3, v3, v3 row_ror:8 row_mask:0xf bank_mask:0xf bound_ctrl:1
	s_nop 1
	v_add_f32_dpp v3, v3, v3 row_ror:4 row_mask:0xf bank_mask:0xf bound_ctrl:1
	s_nop 1
	v_add_f32_dpp v3, v3, v3 quad_perm:[2,3,0,1] row_mask:0xf bank_mask:0xf bound_ctrl:1
	s_nop 1
	v_mov_b32_dpp v4, v3 quad_perm:[1,0,3,2] row_mask:0xf bank_mask:0xf bound_ctrl:1
	s_and_saveexec_b64 s[42:43], s[28:29]
	s_cbranch_execz .LBB0_1012
	v_lshlrev_b32_e32 v0, 7, v0
	v_and_b32_e32 v1, 0x7f, v1
	v_and_or_b32 v0, v0, s49, v1
	v_lshlrev_b32_e32 v1, 2, v0
	global_load_dword v165, v1, s[36:37]
	global_load_dword v161, v1, s[38:39]
	v_add_f32_e32 v1, v3, v4
	v_div_scale_f32 v3, s[44:45], v1, v1, v2
	v_rcp_f32_e32 v4, v3
	s_nop 0
	v_fma_f32 v5, -v3, v4, 1.0
	v_fmac_f32_e32 v4, v5, v4
	v_div_scale_f32 v5, vcc, v2, v1, v2
	v_mul_f32_e32 v6, v5, v4
	v_fma_f32 v7, -v3, v6, v5
	v_fmac_f32_e32 v6, v7, v4
	v_fma_f32 v3, -v3, v6, v5
	v_div_fmas_f32 v3, v3, v4, v6
	v_div_fixup_f32 v1, v3, v1, v2
	ds_write2st64_b32 v164, v0, v1 offset0:12 offset1:14

.LBB0_1024:
	ds_write2st64_b32 v164, v165, v161 offset0:18 offset1:20

.LBB0_1035:
	ds_write2st64_b32 v154, v157, v156 offset0:18 offset1:20
	s_or_b64 exec, exec, s[42:43]
	s_and_saveexec_b64 s[42:43], s[24:25]
	s_cbranch_execz .LBB0_1022
.LBB0_1036:
	ds_write2st64_b32 v158, v159, v155 offset0:18 offset1:20
	s_or_b64 exec, exec, s[42:43]
	s_and_saveexec_b64 s[42:43], s[26:27]
	s_cbranch_execz .LBB0_1023
.LBB0_1037:
	ds_write2st64_b32 v160, v163, v162 offset0:18 offset1:20
	s_or_b64 exec, exec, s[42:43]
	s_and_saveexec_b64 s[42:43], s[28:29]
	s_cbranch_execnz .LBB0_1024
	s_branch .LBB0_1025

.LBB0_1090:
	s_or_b64 exec, exec, s[4:5]
	s_waitcnt lgkmcnt(0)
	s_barrier
	s_mov_b32 s17, 0x8400
	v_ashrrev_i32_e32 v0, 6, v176
	v_mul_lo_u32 v1, v0, s70
	v_add_u32_e32 v92, s2, v1
	v_cmp_gt_i32_e32 vcc, s17, v92
	s_and_saveexec_b64 s[2:3], vcc
	s_cbranch_execz .LBB0_1095
	s_load_dwordx8 s[4:11], s[0:1], 0xe0
	v_and_b32_e32 v3, 31, v176
	v_bfe_u32 v6, v176, 5, 1
	v_lshlrev_b32_e32 v2, 2, v3
	v_lshl_or_b32 v2, v6, 9, v2
	v_lshlrev_b32_e32 v4, 2, v2
	s_waitcnt lgkmcnt(0)
	global_load_dwordx4 v[28:31], v4, s[6:7] offset:1536
	global_load_dwordx4 v[32:35], v4, s[4:5] offset:1536
	global_load_dwordx4 v[36:39], v4, s[6:7] offset:1024
	global_load_dwordx4 v[40:43], v4, s[4:5] offset:1024
	global_load_dwordx4 v[44:47], v4, s[6:7] offset:512
	global_load_dwordx4 v[48:51], v4, s[4:5] offset:512
	global_load_dwordx4 v[52:55], v4, s[6:7]
	global_load_dwordx4 v[56:59], v4, s[4:5]
	s_add_u32 s0, s10, 0x11b47000
	v_ashrrev_i32_e32 v93, 31, v92
	v_and_b32_e32 v1, 63, v176
	s_addc_u32 s1, s11, 0
	v_lshlrev_b64 v[4:5], 9, v[92:93]
	v_mov_b32_e32 v95, 0
	v_lshl_add_u64 v[4:5], s[0:1], 0, v[4:5]
	v_lshlrev_b32_e32 v94, 3, v1
	v_lshl_add_u64 v[4:5], v[4:5], 0, v[94:95]
	s_nop 0
	s_movk_i32 s2, 0x4800
	v_mul_lo_u32 v4, v0, s2
	s_add_u32 s2, s10, 0x1d27000
	s_addc_u32 s3, s11, 0
	v_or_b32_e32 v93, v4, v94
	v_mov_b32_e32 v0, 0x200
	v_lshl_add_u64 v[96:97], s[0:1], 0, v[94:95]
	v_lshlrev_b32_e32 v94, 1, v2
	s_add_u32 s4, s10, 0x1a2004
	v_lshl_or_b32 v117, v3, 3, v0
	v_lshl_add_u64 v[0:1], s[10:11], 0, v[94:95]
	s_mov_b64 s[0:1], 0x6f47000
	s_addc_u32 s5, s11, 0
	v_lshl_add_u64 v[98:99], v[0:1], 0, s[0:1]
	s_add_u32 s6, s8, 0x8000000
	v_lshl_or_b32 v0, v6, 6, v4
	v_lshlrev_b32_e32 v100, 2, v2
	v_lshlrev_b32_e32 v116, 4, v3
	s_addc_u32 s7, s9, 0
	v_mov_b32_e32 v118, v0
	s_mov_b64 s[12:13], 0
	s_mov_b32 s19, 0x83ff
	s_mov_b32 s20, 0x8000
	s_movk_i32 s21, 0x1800
	v_mov_b32_e32 v102, v100
	v_mov_b32_e32 v103, v95
	s_mov_b64 s[14:15], 0x5000
	s_movk_i32 s22, 0x300
	s_mov_b32 s16, 0x3a800000
	s_mov_b32 s18, 0x3f9837f0
	v_mov_b32_e32 v119, 0x3727c5ac
	s_mov_b32 s23, 0x800000
	v_mov_b32_e32 v120, 0x7fc00000
	v_readfirstlane_b32 s40, v92
	v_and_b32_e32 v236, 63, v176
	v_lshl_add_u32 v226, v236, 2, v4
	v_add_u32_e32 v226, 0x800, v226
	v_lshlrev_b32_e32 v236, 3, v236
	s_add_u32 s50, s10, 0x11b47000
	s_addc_u32 s51, s11, 0
	s_mov_b32 s41, s40
	s_mov_b32 s44, 0
	s_mov_b32 s47, s41
	s_cmp_lt_u32 s47, s17
	s_cselect_b32 s48, s47, s40
	s_lshl_b32 s48, s48, 9
	v_add_u32_e32 v237, s48, v236
	global_load_dwordx2 v[228:229], v237, s[50:51]
	s_add_u32 s47, s47, s33
	s_cmp_lt_u32 s47, s17
	s_cselect_b32 s48, s47, s40
	s_lshl_b32 s48, s48, 9
	v_add_u32_e32 v238, s48, v236
	global_load_dwordx2 v[230:231], v238, s[50:51]
	s_add_u32 s47, s47, s33
	s_cmp_lt_u32 s47, s17
	s_cselect_b32 s48, s47, s40
	s_lshl_b32 s48, s48, 9
	v_add_u32_e32 v239, s48, v236
	global_load_dwordx2 v[232:233], v239, s[50:51]
	s_add_u32 s47, s47, s33
	s_cmp_lt_u32 s47, s17
	s_cselect_b32 s48, s47, s40
	s_lshl_b32 s48, s48, 9
	v_add_u32_e32 v240, s48, v236
	global_load_dwordx2 v[234:235], v240, s[50:51]
.Lg2_group:
	s_waitcnt vmcnt(0)
	ds_write_b64 v93, v[228:229]
	ds_write_b64 v93, v[230:231] offset:512
	ds_write_b64 v93, v[232:233] offset:1024
	ds_write_b64 v93, v[234:235] offset:1536
	s_lshl_b32 s46, s33, 2
	s_add_u32 s46, s41, s46
	s_mov_b32 s47, s46
	s_cmp_lt_u32 s47, s17
	s_cselect_b32 s48, s47, s40
	s_lshl_b32 s48, s48, 9
	v_add_u32_e32 v237, s48, v236
	global_load_dwordx2 v[228:229], v237, s[50:51]
	s_add_u32 s47, s47, s33
	s_cmp_lt_u32 s47, s17
	s_cselect_b32 s48, s47, s40
	s_lshl_b32 s48, s48, 9
	v_add_u32_e32 v238, s48, v236
	global_load_dwordx2 v[230:231], v238, s[50:51]
	s_add_u32 s47, s47, s33
	s_cmp_lt_u32 s47, s17
	s_cselect_b32 s48, s47, s40
	s_lshl_b32 s48, s48, 9
	v_add_u32_e32 v239, s48, v236
	global_load_dwordx2 v[232:233], v239, s[50:51]
	s_add_u32 s47, s47, s33
	s_cmp_lt_u32 s47, s17
	s_cselect_b32 s48, s47, s40
	s_lshl_b32 s48, s48, 9
	v_add_u32_e32 v240, s48, v236
	global_load_dwordx2 v[234:235], v240, s[50:51]
	s_waitcnt lgkmcnt(0)
	s_mov_b32 s43, 0
.Lg2_sweep:
	s_mov_b32 s42, 0
	s_mov_b32 s45, s41
.Lg2_tok:
	s_cmp_ge_u32 s45, s17
	s_cbranch_scc1 .Lg2_sweep_done
	s_xor_b32 s46, s43, s44
	s_lshl_b32 s46, s46, 8
	s_lshl_b32 s47, s42, 9
	s_add_u32 s46, s46, s47
	v_add_u32_e32 v101, s46, v118
	s_lshl_b32 s47, s42, 12
	v_add_u32_e32 v227, s47, v226
	s_movk_i32 s24, 0x20
	s_cmp_eq_u32 s43, 0
	s_cbranch_scc0 .Lg2_tok_s2
	v_mov_b32_e32 v133, 0
	v_mov_b32_e32 v131, 0
	v_mov_b32_e32 v129, 0
	v_mov_b32_e32 v128, 0
	v_mov_b32_e32 v127, 0
	v_mov_b32_e32 v125, 0
	v_mov_b32_e32 v123, 0
	v_mov_b32_e32 v121, 0
	v_mov_b32_e32 v136, 0
	v_mov_b32_e32 v135, 0
	v_mov_b32_e32 v134, 0
	v_mov_b32_e32 v132, 0
	v_mov_b32_e32 v130, 0
	v_mov_b32_e32 v126, 0
	v_mov_b32_e32 v124, 0
	v_mov_b32_e32 v122, 0
	s_branch .LBB0_1093
.Lg2_tok_s2:
	v_mov_b32_e32 v0, s45
	v_add_u32_e32 v94, 0xffff8000, v0
	v_lshrrev_b32_e32 v7, 5, v94
	v_lshrrev_b32_e32 v6, 11, v0
	v_add_u32_e32 v7, 16, v7
	v_cmp_gt_i32_e64 s[0:1], s20, v0
	s_nop 1
	v_cndmask_b32_e64 v6, v7, v6, s[0:1]
	v_mul_lo_u32 v6, v6, s21
	v_ashrrev_i32_e32 v7, 31, v6
	v_lshl_add_u64 v[6:7], v[6:7], 2, s[10:11]
	v_lshl_add_u64 v[6:7], v[6:7], 0, v[102:103]
	v_ashrrev_i32_e32 v1, 31, v0
	v_lshl_add_u64 v[8:9], v[6:7], 0, s[14:15]
	v_add_co_u32_e32 v6, vcc, 0x5000, v6
	v_lshlrev_b64 v[4:5], 11, v[0:1]
	v_addc_co_u32_e32 v7, vcc, 0, v7, vcc
	v_lshl_add_u64 v[4:5], v[98:99], 0, v[4:5]
	global_load_dwordx4 v[68:71], v[6:7], off
	global_load_dwordx2 v[112:113], v[4:5], off
	global_load_dwordx2 v[110:111], v[4:5], off offset:256
	global_load_dwordx2 v[108:109], v[4:5], off offset:512
	global_load_dwordx4 v[72:75], v[8:9], off offset:512
	global_load_dwordx2 v[106:107], v[4:5], off offset:768
	global_load_dwordx4 v[64:67], v[8:9], off offset:1024
	global_load_dwordx4 v[60:63], v[8:9], off offset:1536
	v_lshlrev_b64 v[114:115], 10, v[0:1]
	ds_read_b32 v121, v227
	ds_read2st64_b32 v[122:123], v227 offset0:1 offset1:2
	ds_read2st64_b32 v[124:125], v227 offset0:3 offset1:4
	ds_read2st64_b32 v[126:127], v227 offset0:5 offset1:6
	ds_read2st64_b32 v[128:129], v227 offset0:7 offset1:8
	ds_read2st64_b32 v[130:131], v227 offset0:9 offset1:10
	ds_read2st64_b32 v[132:133], v227 offset0:11 offset1:12
	ds_read2st64_b32 v[134:135], v227 offset0:13 offset1:14
	ds_read_b32 v136, v227 offset:3840
	s_waitcnt lgkmcnt(0)
.LBB0_1093:
	ds_read_b128 v[88:91], v101
	ds_read_b128 v[84:87], v101 offset:16
	ds_read_b128 v[80:83], v101 offset:32
	ds_read_b128 v[76:79], v101 offset:48
	s_add_i32 s24, s24, 32
	s_waitcnt lgkmcnt(3)
	v_and_b32_e32 v0, 0xffff, v88
	v_and_b32_e32 v1, 0xffff, v89
	v_and_b32_e32 v2, 0xffff, v90
	v_and_b32_e32 v3, 0xffff, v91
	s_waitcnt lgkmcnt(2)
	v_and_b32_e32 v4, 0xffff, v84
	v_and_b32_e32 v5, 0xffff, v85
	v_and_b32_e32 v6, 0xffff, v86
	v_and_b32_e32 v7, 0xffff, v87
	s_waitcnt lgkmcnt(1)
	v_and_b32_e32 v8, 0xffff, v80
	v_and_b32_e32 v9, 0xffff, v81
	v_and_b32_e32 v11, 0xffff, v83
	s_waitcnt lgkmcnt(0)
	v_and_b32_e32 v12, 0xffff, v76
	v_and_b32_e32 v13, 0xffff, v77
	v_and_b32_e32 v10, 0xffff, v82
	v_and_b32_e32 v14, 0xffff, v78
	v_and_b32_e32 v15, 0xffff, v79
	v_mad_u32_u24 v16, v0, s22, v116
	v_mad_u32_u24 v17, v1, s22, v117
	v_mad_u32_u24 v18, v2, s22, v116
	v_mad_u32_u24 v19, v3, s22, v116
	v_mad_u32_u24 v22, v4, s22, v116
	v_mad_u32_u24 v23, v5, s22, v116
	v_mad_u32_u24 v24, v6, s22, v116
	v_mad_u32_u24 v25, v7, s22, v116
	v_mad_u32_u24 v26, v8, s22, v116
	v_mad_u32_u24 v27, v9, s22, v116
	v_mad_u32_u24 v204, v11, s22, v116
	v_mad_u32_u24 v210, v12, s22, v116
	v_mad_u32_u24 v216, v13, s22, v116
	v_mad_u32_u24 v0, v0, s22, v117
	v_mad_u32_u24 v2, v2, s22, v117
	v_mad_u32_u24 v3, v3, s22, v117
	v_mad_u32_u24 v4, v4, s22, v117
	v_mad_u32_u24 v5, v5, s22, v117
	v_mad_u32_u24 v6, v6, s22, v117
	v_mad_u32_u24 v7, v7, s22, v117
	v_mad_u32_u24 v8, v8, s22, v117
	v_mad_u32_u24 v9, v9, s22, v117
	v_mad_u32_u24 v137, v10, s22, v116
	v_mad_u32_u24 v10, v10, s22, v117
	v_mad_u32_u24 v11, v11, s22, v117
	v_mad_u32_u24 v12, v12, s22, v117
	v_mad_u32_u24 v13, v13, s22, v117
	v_mad_u32_u24 v222, v14, s22, v116
	v_mad_u32_u24 v14, v14, s22, v117
	v_mad_u32_u24 v223, v15, s22, v116
	v_mad_u32_u24 v15, v15, s22, v117
	v_mad_u32_u24 v1, v1, s22, v116
	global_load_dwordx4 v[138:141], v16, s[2:3]
	global_load_dwordx2 v[142:143], v0, s[2:3]
	global_load_dwordx4 v[144:147], v1, s[2:3]
	global_load_dwordx2 v[148:149], v17, s[2:3]
	global_load_dwordx4 v[150:153], v18, s[2:3]
	global_load_dwordx2 v[154:155], v2, s[2:3]
	global_load_dwordx4 v[156:159], v19, s[2:3]
	global_load_dwordx2 v[160:161], v3, s[2:3]
	global_load_dwordx2 v[20:21], v15, s[2:3]
	global_load_dwordx4 v[162:165], v22, s[2:3]
	global_load_dwordx2 v[166:167], v4, s[2:3]
	global_load_dwordx4 v[168:171], v23, s[2:3]
	global_load_dwordx2 v[172:173], v5, s[2:3]
	global_load_dwordx4 v[174:177], v24, s[2:3]
	global_load_dwordx2 v[178:179], v6, s[2:3]
	global_load_dwordx4 v[180:183], v25, s[2:3]
	global_load_dwordx2 v[184:185], v7, s[2:3]
	global_load_dwordx4 v[186:189], v26, s[2:3]
	global_load_dwordx2 v[190:191], v8, s[2:3]
	global_load_dwordx4 v[192:195], v27, s[2:3]
	global_load_dwordx2 v[196:197], v9, s[2:3]
	global_load_dwordx4 v[198:201], v137, s[2:3]
	global_load_dwordx2 v[202:203], v10, s[2:3]
	s_nop 0
	global_load_dwordx4 v[204:207], v204, s[2:3]
	s_nop 0
	global_load_dwordx2 v[208:209], v11, s[2:3]
	s_nop 0
	global_load_dwordx4 v[210:213], v210, s[2:3]
	s_nop 0
	global_load_dwordx2 v[214:215], v12, s[2:3]
	s_nop 0
	global_load_dwordx4 v[216:219], v216, s[2:3]
	s_nop 0
	global_load_dwordx2 v[220:221], v13, s[2:3]
	global_load_dwordx4 v[22:25], v222, s[2:3]
	global_load_dwordx2 v[26:27], v14, s[2:3]
	global_load_dwordx4 v[16:19], v223, s[2:3]
	v_add_u32_e32 v101, 0x80, v101
	s_cmpk_lt_u32 s24, 0x60
	s_waitcnt vmcnt(30)
	v_cvt_scalef32_pk32_f16_fp6 v[0:15], v[138:143], 1.0
	v_pk_fma_f16 v133, v88, v0, v133 op_sel:[1,0,0]
	v_pk_fma_f16 v131, v88, v1, v131 op_sel:[1,0,0]
	v_pk_fma_f16 v129, v88, v2, v129 op_sel:[1,0,0]
	v_pk_fma_f16 v128, v88, v3, v128 op_sel:[1,0,0]
	v_pk_fma_f16 v127, v88, v4, v127 op_sel:[1,0,0]
	v_pk_fma_f16 v125, v88, v5, v125 op_sel:[1,0,0]
	v_pk_fma_f16 v123, v88, v6, v123 op_sel:[1,0,0]
	v_pk_fma_f16 v121, v88, v7, v121 op_sel:[1,0,0]
	v_pk_fma_f16 v136, v88, v8, v136 op_sel:[1,0,0]
	v_pk_fma_f16 v135, v88, v9, v135 op_sel:[1,0,0]
	v_pk_fma_f16 v134, v88, v10, v134 op_sel:[1,0,0]
	v_pk_fma_f16 v132, v88, v11, v132 op_sel:[1,0,0]
	v_pk_fma_f16 v130, v88, v12, v130 op_sel:[1,0,0]
	v_pk_fma_f16 v126, v88, v13, v126 op_sel:[1,0,0]
	v_pk_fma_f16 v124, v88, v14, v124 op_sel:[1,0,0]
	v_pk_fma_f16 v88, v88, v15, v122 op_sel:[1,0,0]
	s_waitcnt vmcnt(29)
	s_waitcnt vmcnt(28)
	v_cvt_scalef32_pk32_f16_fp6 v[0:15], v[144:149], 1.0
	v_pk_fma_f16 v122, v89, v0, v133 op_sel:[1,0,0]
	v_pk_fma_f16 v131, v89, v1, v131 op_sel:[1,0,0]
	v_pk_fma_f16 v129, v89, v2, v129 op_sel:[1,0,0]
	v_pk_fma_f16 v128, v89, v3, v128 op_sel:[1,0,0]
	v_pk_fma_f16 v127, v89, v4, v127 op_sel:[1,0,0]
	v_pk_fma_f16 v125, v89, v5, v125 op_sel:[1,0,0]
	v_pk_fma_f16 v123, v89, v6, v123 op_sel:[1,0,0]
	v_pk_fma_f16 v121, v89, v7, v121 op_sel:[1,0,0]
	v_pk_fma_f16 v133, v89, v8, v136 op_sel:[1,0,0]
	v_pk_fma_f16 v135, v89, v9, v135 op_sel:[1,0,0]
	v_pk_fma_f16 v134, v89, v10, v134 op_sel:[1,0,0]
	v_pk_fma_f16 v132, v89, v11, v132 op_sel:[1,0,0]
	v_pk_fma_f16 v130, v89, v12, v130 op_sel:[1,0,0]
	v_pk_fma_f16 v126, v89, v13, v126 op_sel:[1,0,0]
	v_pk_fma_f16 v124, v89, v14, v124 op_sel:[1,0,0]
	v_pk_fma_f16 v88, v89, v15, v88 op_sel:[1,0,0]
	s_waitcnt vmcnt(27)
	s_waitcnt vmcnt(26)
	v_cvt_scalef32_pk32_f16_fp6 v[0:15], v[150:155], 1.0
	v_pk_fma_f16 v89, v90, v0, v122 op_sel:[1,0,0]
	v_pk_fma_f16 v122, v90, v1, v131 op_sel:[1,0,0]
	v_pk_fma_f16 v129, v90, v2, v129 op_sel:[1,0,0]
	v_pk_fma_f16 v128, v90, v3, v128 op_sel:[1,0,0]
	v_pk_fma_f16 v127, v90, v4, v127 op_sel:[1,0,0]
	v_pk_fma_f16 v125, v90, v5, v125 op_sel:[1,0,0]
	v_pk_fma_f16 v123, v90, v6, v123 op_sel:[1,0,0]
	v_pk_fma_f16 v121, v90, v7, v121 op_sel:[1,0,0]
	v_pk_fma_f16 v131, v90, v8, v133 op_sel:[1,0,0]
	v_pk_fma_f16 v133, v90, v9, v135 op_sel:[1,0,0]
	v_pk_fma_f16 v134, v90, v10, v134 op_sel:[1,0,0]
	v_pk_fma_f16 v132, v90, v11, v132 op_sel:[1,0,0]
	v_pk_fma_f16 v130, v90, v12, v130 op_sel:[1,0,0]
	v_pk_fma_f16 v126, v90, v13, v126 op_sel:[1,0,0]
	v_pk_fma_f16 v124, v90, v14, v124 op_sel:[1,0,0]
	v_pk_fma_f16 v88, v90, v15, v88 op_sel:[1,0,0]
	s_waitcnt vmcnt(25)
	s_waitcnt vmcnt(24)
	v_cvt_scalef32_pk32_f16_fp6 v[0:15], v[156:161], 1.0
	v_pk_fma_f16 v89, v91, v0, v89 op_sel:[1,0,0]
	v_pk_fma_f16 v90, v91, v1, v122 op_sel:[1,0,0]
	v_pk_fma_f16 v122, v91, v2, v129 op_sel:[1,0,0]
	v_pk_fma_f16 v128, v91, v3, v128 op_sel:[1,0,0]
	v_pk_fma_f16 v127, v91, v4, v127 op_sel:[1,0,0]
	v_pk_fma_f16 v125, v91, v5, v125 op_sel:[1,0,0]
	v_pk_fma_f16 v123, v91, v6, v123 op_sel:[1,0,0]
	v_pk_fma_f16 v121, v91, v7, v121 op_sel:[1,0,0]
	v_pk_fma_f16 v129, v91, v8, v131 op_sel:[1,0,0]
	v_pk_fma_f16 v131, v91, v9, v133 op_sel:[1,0,0]
	v_pk_fma_f16 v133, v91, v10, v134 op_sel:[1,0,0]
	v_pk_fma_f16 v132, v91, v11, v132 op_sel:[1,0,0]
	v_pk_fma_f16 v130, v91, v12, v130 op_sel:[1,0,0]
	v_pk_fma_f16 v126, v91, v13, v126 op_sel:[1,0,0]
	v_pk_fma_f16 v124, v91, v14, v124 op_sel:[1,0,0]
	v_pk_fma_f16 v88, v91, v15, v88 op_sel:[1,0,0]
	s_waitcnt vmcnt(22)
	s_waitcnt vmcnt(21)
	v_cvt_scalef32_pk32_f16_fp6 v[0:15], v[162:167], 1.0
	v_pk_fma_f16 v89, v84, v0, v89 op_sel:[1,0,0]
	v_pk_fma_f16 v90, v84, v1, v90 op_sel:[1,0,0]
	v_pk_fma_f16 v91, v84, v2, v122 op_sel:[1,0,0]
	v_pk_fma_f16 v122, v84, v3, v128 op_sel:[1,0,0]
	v_pk_fma_f16 v127, v84, v4, v127 op_sel:[1,0,0]
	v_pk_fma_f16 v125, v84, v5, v125 op_sel:[1,0,0]
	v_pk_fma_f16 v123, v84, v6, v123 op_sel:[1,0,0]
	v_pk_fma_f16 v121, v84, v7, v121 op_sel:[1,0,0]
	v_pk_fma_f16 v128, v84, v8, v129 op_sel:[1,0,0]
	v_pk_fma_f16 v129, v84, v9, v131 op_sel:[1,0,0]
	v_pk_fma_f16 v131, v84, v10, v133 op_sel:[1,0,0]
	v_pk_fma_f16 v132, v84, v11, v132 op_sel:[1,0,0]
	v_pk_fma_f16 v130, v84, v12, v130 op_sel:[1,0,0]
	v_pk_fma_f16 v126, v84, v13, v126 op_sel:[1,0,0]
	v_pk_fma_f16 v124, v84, v14, v124 op_sel:[1,0,0]
	v_pk_fma_f16 v84, v84, v15, v88 op_sel:[1,0,0]
	s_waitcnt vmcnt(20)
	s_waitcnt vmcnt(19)
	v_cvt_scalef32_pk32_f16_fp6 v[0:15], v[168:173], 1.0
	v_pk_fma_f16 v88, v85, v0, v89 op_sel:[1,0,0]
	v_pk_fma_f16 v89, v85, v1, v90 op_sel:[1,0,0]
	v_pk_fma_f16 v90, v85, v2, v91 op_sel:[1,0,0]
	v_pk_fma_f16 v91, v85, v3, v122 op_sel:[1,0,0]
	v_pk_fma_f16 v122, v85, v4, v127 op_sel:[1,0,0]
	v_pk_fma_f16 v125, v85, v5, v125 op_sel:[1,0,0]
	v_pk_fma_f16 v123, v85, v6, v123 op_sel:[1,0,0]
	v_pk_fma_f16 v121, v85, v7, v121 op_sel:[1,0,0]
	v_pk_fma_f16 v127, v85, v8, v128 op_sel:[1,0,0]
	v_pk_fma_f16 v128, v85, v9, v129 op_sel:[1,0,0]
	v_pk_fma_f16 v129, v85, v10, v131 op_sel:[1,0,0]
	v_pk_fma_f16 v131, v85, v11, v132 op_sel:[1,0,0]
	v_pk_fma_f16 v130, v85, v12, v130 op_sel:[1,0,0]
	v_pk_fma_f16 v126, v85, v13, v126 op_sel:[1,0,0]
	v_pk_fma_f16 v124, v85, v14, v124 op_sel:[1,0,0]
	v_pk_fma_f16 v84, v85, v15, v84 op_sel:[1,0,0]
	s_waitcnt vmcnt(18)
	s_waitcnt vmcnt(17)
	v_cvt_scalef32_pk32_f16_fp6 v[0:15], v[174:179], 1.0
	v_pk_fma_f16 v85, v86, v0, v88 op_sel:[1,0,0]
	v_pk_fma_f16 v88, v86, v1, v89 op_sel:[1,0,0]
	v_pk_fma_f16 v89, v86, v2, v90 op_sel:[1,0,0]
	v_pk_fma_f16 v90, v86, v3, v91 op_sel:[1,0,0]
	v_pk_fma_f16 v91, v86, v4, v122 op_sel:[1,0,0]
	v_pk_fma_f16 v122, v86, v5, v125 op_sel:[1,0,0]
	v_pk_fma_f16 v123, v86, v6, v123 op_sel:[1,0,0]
	v_pk_fma_f16 v121, v86, v7, v121 op_sel:[1,0,0]
	v_pk_fma_f16 v125, v86, v8, v127 op_sel:[1,0,0]
	v_pk_fma_f16 v127, v86, v9, v128 op_sel:[1,0,0]
	v_pk_fma_f16 v128, v86, v10, v129 op_sel:[1,0,0]
	v_pk_fma_f16 v129, v86, v11, v131 op_sel:[1,0,0]
	v_pk_fma_f16 v130, v86, v12, v130 op_sel:[1,0,0]
	v_pk_fma_f16 v126, v86, v13, v126 op_sel:[1,0,0]
	v_pk_fma_f16 v124, v86, v14, v124 op_sel:[1,0,0]
	v_pk_fma_f16 v84, v86, v15, v84 op_sel:[1,0,0]
	s_waitcnt vmcnt(16)
	s_waitcnt vmcnt(15)
	v_cvt_scalef32_pk32_f16_fp6 v[0:15], v[180:185], 1.0
	v_pk_fma_f16 v85, v87, v0, v85 op_sel:[1,0,0]
	v_pk_fma_f16 v86, v87, v1, v88 op_sel:[1,0,0]
	v_pk_fma_f16 v88, v87, v2, v89 op_sel:[1,0,0]
	v_pk_fma_f16 v89, v87, v3, v90 op_sel:[1,0,0]
	v_pk_fma_f16 v90, v87, v4, v91 op_sel:[1,0,0]
	v_pk_fma_f16 v91, v87, v5, v122 op_sel:[1,0,0]
	v_pk_fma_f16 v122, v87, v6, v123 op_sel:[1,0,0]
	v_pk_fma_f16 v121, v87, v7, v121 op_sel:[1,0,0]
	v_pk_fma_f16 v123, v87, v8, v125 op_sel:[1,0,0]
	v_pk_fma_f16 v125, v87, v9, v127 op_sel:[1,0,0]
	v_pk_fma_f16 v127, v87, v10, v128 op_sel:[1,0,0]
	v_pk_fma_f16 v128, v87, v11, v129 op_sel:[1,0,0]
	v_pk_fma_f16 v129, v87, v12, v130 op_sel:[1,0,0]
	v_pk_fma_f16 v126, v87, v13, v126 op_sel:[1,0,0]
	v_pk_fma_f16 v124, v87, v14, v124 op_sel:[1,0,0]
	v_pk_fma_f16 v84, v87, v15, v84 op_sel:[1,0,0]
	s_waitcnt vmcnt(14)
	s_waitcnt vmcnt(13)
	v_cvt_scalef32_pk32_f16_fp6 v[0:15], v[186:191], 1.0
	v_pk_fma_f16 v85, v80, v0, v85 op_sel:[1,0,0]
	v_pk_fma_f16 v86, v80, v1, v86 op_sel:[1,0,0]
	v_pk_fma_f16 v87, v80, v2, v88 op_sel:[1,0,0]
	v_pk_fma_f16 v88, v80, v3, v89 op_sel:[1,0,0]
	v_pk_fma_f16 v89, v80, v4, v90 op_sel:[1,0,0]
	v_pk_fma_f16 v90, v80, v5, v91 op_sel:[1,0,0]
	v_pk_fma_f16 v91, v80, v6, v122 op_sel:[1,0,0]
	v_pk_fma_f16 v121, v80, v7, v121 op_sel:[1,0,0]
	v_pk_fma_f16 v122, v80, v8, v123 op_sel:[1,0,0]
	v_pk_fma_f16 v123, v80, v9, v125 op_sel:[1,0,0]
	v_pk_fma_f16 v125, v80, v10, v127 op_sel:[1,0,0]
	v_pk_fma_f16 v127, v80, v11, v128 op_sel:[1,0,0]
	v_pk_fma_f16 v128, v80, v12, v129 op_sel:[1,0,0]
	v_pk_fma_f16 v126, v80, v13, v126 op_sel:[1,0,0]
	v_pk_fma_f16 v124, v80, v14, v124 op_sel:[1,0,0]
	v_pk_fma_f16 v80, v80, v15, v84 op_sel:[1,0,0]
	s_waitcnt vmcnt(12)
	s_waitcnt vmcnt(11)
	v_cvt_scalef32_pk32_f16_fp6 v[0:15], v[192:197], 1.0
	v_pk_fma_f16 v84, v81, v0, v85 op_sel:[1,0,0]
	v_pk_fma_f16 v85, v81, v1, v86 op_sel:[1,0,0]
	v_pk_fma_f16 v86, v81, v2, v87 op_sel:[1,0,0]
	v_pk_fma_f16 v87, v81, v3, v88 op_sel:[1,0,0]
	v_pk_fma_f16 v88, v81, v4, v89 op_sel:[1,0,0]
	v_pk_fma_f16 v89, v81, v5, v90 op_sel:[1,0,0]
	v_pk_fma_f16 v90, v81, v6, v91 op_sel:[1,0,0]
	v_pk_fma_f16 v91, v81, v7, v121 op_sel:[1,0,0]
	v_pk_fma_f16 v121, v81, v8, v122 op_sel:[1,0,0]
	v_pk_fma_f16 v122, v81, v9, v123 op_sel:[1,0,0]
	v_pk_fma_f16 v123, v81, v10, v125 op_sel:[1,0,0]
	v_pk_fma_f16 v125, v81, v11, v127 op_sel:[1,0,0]
	v_pk_fma_f16 v127, v81, v12, v128 op_sel:[1,0,0]
	v_pk_fma_f16 v126, v81, v13, v126 op_sel:[1,0,0]
	v_pk_fma_f16 v124, v81, v14, v124 op_sel:[1,0,0]
	v_pk_fma_f16 v80, v81, v15, v80 op_sel:[1,0,0]
	s_waitcnt vmcnt(10)
	s_waitcnt vmcnt(9)
	v_cvt_scalef32_pk32_f16_fp6 v[0:15], v[198:203], 1.0
	v_pk_fma_f16 v81, v82, v0, v84 op_sel:[1,0,0]
	v_pk_fma_f16 v84, v82, v1, v85 op_sel:[1,0,0]
	v_pk_fma_f16 v85, v82, v2, v86 op_sel:[1,0,0]
	v_pk_fma_f16 v86, v82, v3, v87 op_sel:[1,0,0]
	v_pk_fma_f16 v87, v82, v4, v88 op_sel:[1,0,0]
	v_pk_fma_f16 v88, v82, v5, v89 op_sel:[1,0,0]
	v_pk_fma_f16 v89, v82, v6, v90 op_sel:[1,0,0]
	v_pk_fma_f16 v90, v82, v7, v91 op_sel:[1,0,0]
	v_pk_fma_f16 v91, v82, v8, v121 op_sel:[1,0,0]
	v_pk_fma_f16 v121, v82, v9, v122 op_sel:[1,0,0]
	v_pk_fma_f16 v122, v82, v10, v123 op_sel:[1,0,0]
	v_pk_fma_f16 v123, v82, v11, v125 op_sel:[1,0,0]
	v_pk_fma_f16 v125, v82, v12, v127 op_sel:[1,0,0]
	v_pk_fma_f16 v126, v82, v13, v126 op_sel:[1,0,0]
	v_pk_fma_f16 v124, v82, v14, v124 op_sel:[1,0,0]
	v_pk_fma_f16 v80, v82, v15, v80 op_sel:[1,0,0]
	s_waitcnt vmcnt(8)
	s_waitcnt vmcnt(7)
	v_cvt_scalef32_pk32_f16_fp6 v[0:15], v[204:209], 1.0
	v_pk_fma_f16 v81, v83, v0, v81 op_sel:[1,0,0]
	v_pk_fma_f16 v82, v83, v1, v84 op_sel:[1,0,0]
	v_pk_fma_f16 v84, v83, v2, v85 op_sel:[1,0,0]
	v_pk_fma_f16 v85, v83, v3, v86 op_sel:[1,0,0]
	v_pk_fma_f16 v86, v83, v4, v87 op_sel:[1,0,0]
	v_pk_fma_f16 v87, v83, v5, v88 op_sel:[1,0,0]
	v_pk_fma_f16 v88, v83, v6, v89 op_sel:[1,0,0]
	v_pk_fma_f16 v89, v83, v7, v90 op_sel:[1,0,0]
	v_pk_fma_f16 v90, v83, v8, v91 op_sel:[1,0,0]
	v_pk_fma_f16 v91, v83, v9, v121 op_sel:[1,0,0]
	v_pk_fma_f16 v121, v83, v10, v122 op_sel:[1,0,0]
	v_pk_fma_f16 v122, v83, v11, v123 op_sel:[1,0,0]
	v_pk_fma_f16 v123, v83, v12, v125 op_sel:[1,0,0]
	v_pk_fma_f16 v125, v83, v13, v126 op_sel:[1,0,0]
	v_pk_fma_f16 v124, v83, v14, v124 op_sel:[1,0,0]
	v_pk_fma_f16 v80, v83, v15, v80 op_sel:[1,0,0]
	s_waitcnt vmcnt(6)
	s_waitcnt vmcnt(5)
	v_cvt_scalef32_pk32_f16_fp6 v[0:15], v[210:215], 1.0
	v_pk_fma_f16 v81, v76, v0, v81 op_sel:[1,0,0]
	v_pk_fma_f16 v82, v76, v1, v82 op_sel:[1,0,0]
	v_pk_fma_f16 v83, v76, v2, v84 op_sel:[1,0,0]
	v_pk_fma_f16 v84, v76, v3, v85 op_sel:[1,0,0]
	v_pk_fma_f16 v85, v76, v4, v86 op_sel:[1,0,0]
	v_pk_fma_f16 v86, v76, v5, v87 op_sel:[1,0,0]
	v_pk_fma_f16 v87, v76, v6, v88 op_sel:[1,0,0]
	v_pk_fma_f16 v88, v76, v7, v89 op_sel:[1,0,0]
	v_pk_fma_f16 v89, v76, v8, v90 op_sel:[1,0,0]
	v_pk_fma_f16 v90, v76, v9, v91 op_sel:[1,0,0]
	v_pk_fma_f16 v91, v76, v10, v121 op_sel:[1,0,0]
	v_pk_fma_f16 v121, v76, v11, v122 op_sel:[1,0,0]
	v_pk_fma_f16 v122, v76, v12, v123 op_sel:[1,0,0]
	v_pk_fma_f16 v123, v76, v13, v125 op_sel:[1,0,0]
	v_pk_fma_f16 v124, v76, v14, v124 op_sel:[1,0,0]
	v_pk_fma_f16 v76, v76, v15, v80 op_sel:[1,0,0]
	s_waitcnt vmcnt(4)
	s_waitcnt vmcnt(3)
	v_cvt_scalef32_pk32_f16_fp6 v[0:15], v[216:221], 1.0
	v_pk_fma_f16 v80, v77, v0, v81 op_sel:[1,0,0]
	v_pk_fma_f16 v81, v77, v1, v82 op_sel:[1,0,0]
	v_pk_fma_f16 v82, v77, v2, v83 op_sel:[1,0,0]
	v_pk_fma_f16 v83, v77, v3, v84 op_sel:[1,0,0]
	v_pk_fma_f16 v84, v77, v4, v85 op_sel:[1,0,0]
	v_pk_fma_f16 v85, v77, v5, v86 op_sel:[1,0,0]
	v_pk_fma_f16 v86, v77, v6, v87 op_sel:[1,0,0]
	v_pk_fma_f16 v87, v77, v7, v88 op_sel:[1,0,0]
	v_pk_fma_f16 v88, v77, v8, v89 op_sel:[1,0,0]
	v_pk_fma_f16 v89, v77, v9, v90 op_sel:[1,0,0]
	v_pk_fma_f16 v90, v77, v10, v91 op_sel:[1,0,0]
	v_pk_fma_f16 v91, v77, v11, v121 op_sel:[1,0,0]
	v_pk_fma_f16 v121, v77, v12, v122 op_sel:[1,0,0]
	v_pk_fma_f16 v122, v77, v13, v123 op_sel:[1,0,0]
	v_pk_fma_f16 v123, v77, v14, v124 op_sel:[1,0,0]
	v_pk_fma_f16 v76, v77, v15, v76 op_sel:[1,0,0]
	s_waitcnt vmcnt(2)
	s_waitcnt vmcnt(1)
	v_cvt_scalef32_pk32_f16_fp6 v[0:15], v[22:27], 1.0
	v_pk_fma_f16 v22, v78, v0, v80 op_sel:[1,0,0]
	v_pk_fma_f16 v23, v78, v1, v81 op_sel:[1,0,0]
	v_pk_fma_f16 v24, v78, v2, v82 op_sel:[1,0,0]
	v_pk_fma_f16 v25, v78, v3, v83 op_sel:[1,0,0]
	v_pk_fma_f16 v26, v78, v4, v84 op_sel:[1,0,0]
	v_pk_fma_f16 v27, v78, v5, v85 op_sel:[1,0,0]
	v_pk_fma_f16 v77, v78, v6, v86 op_sel:[1,0,0]
	v_pk_fma_f16 v80, v78, v7, v87 op_sel:[1,0,0]
	v_pk_fma_f16 v81, v78, v8, v88 op_sel:[1,0,0]
	v_pk_fma_f16 v82, v78, v9, v89 op_sel:[1,0,0]
	v_pk_fma_f16 v83, v78, v10, v90 op_sel:[1,0,0]
	v_pk_fma_f16 v84, v78, v11, v91 op_sel:[1,0,0]
	v_pk_fma_f16 v85, v78, v12, v121 op_sel:[1,0,0]
	v_pk_fma_f16 v86, v78, v13, v122 op_sel:[1,0,0]
	v_pk_fma_f16 v87, v78, v14, v123 op_sel:[1,0,0]
	v_pk_fma_f16 v76, v78, v15, v76 op_sel:[1,0,0]
	s_waitcnt vmcnt(0)
	s_nop 0
	v_cvt_scalef32_pk32_f16_fp6 v[0:15], v[16:21], 1.0
	v_pk_fma_f16 v133, v79, v0, v22 op_sel:[1,0,0]
	v_pk_fma_f16 v131, v79, v1, v23 op_sel:[1,0,0]
	v_pk_fma_f16 v129, v79, v2, v24 op_sel:[1,0,0]
	v_pk_fma_f16 v128, v79, v3, v25 op_sel:[1,0,0]
	v_pk_fma_f16 v127, v79, v4, v26 op_sel:[1,0,0]
	v_pk_fma_f16 v125, v79, v5, v27 op_sel:[1,0,0]
	v_pk_fma_f16 v123, v79, v6, v77 op_sel:[1,0,0]
	v_pk_fma_f16 v121, v79, v7, v80 op_sel:[1,0,0]
	v_pk_fma_f16 v136, v79, v8, v81 op_sel:[1,0,0]
	v_pk_fma_f16 v135, v79, v9, v82 op_sel:[1,0,0]
	v_pk_fma_f16 v134, v79, v10, v83 op_sel:[1,0,0]
	v_pk_fma_f16 v132, v79, v11, v84 op_sel:[1,0,0]
	v_pk_fma_f16 v130, v79, v12, v85 op_sel:[1,0,0]
	v_pk_fma_f16 v126, v79, v13, v86 op_sel:[1,0,0]
	v_pk_fma_f16 v124, v79, v14, v87 op_sel:[1,0,0]
	v_pk_fma_f16 v122, v79, v15, v76 op_sel:[1,0,0]
	s_cbranch_scc1 .LBB0_1093
	s_cmp_eq_u32 s43, 0
	s_cbranch_scc1 .Lg2_save
	global_load_dword v82, v95, s[4:5]
	v_permlane32_swap_b32_e32 v133, v136
	v_permlane32_swap_b32_e32 v131, v135
	v_permlane32_swap_b32_e32 v129, v134
	v_cvt_f32_f16_e32 v14, v133
	v_cvt_f32_f16_sdwa v15, v133 dst_sel:DWORD dst_unused:UNUSED_PAD src0_sel:WORD_1
	v_cvt_f32_f16_e32 v16, v136
	v_cvt_f32_f16_sdwa v17, v136 dst_sel:DWORD dst_unused:UNUSED_PAD src0_sel:WORD_1
	v_cvt_f32_f16_e32 v18, v131
	v_cvt_f32_f16_sdwa v19, v131 dst_sel:DWORD dst_unused:UNUSED_PAD src0_sel:WORD_1
	v_cvt_f32_f16_e32 v20, v135
	v_cvt_f32_f16_sdwa v21, v135 dst_sel:DWORD dst_unused:UNUSED_PAD src0_sel:WORD_1
	v_cvt_f32_f16_e32 v22, v129
	v_cvt_f32_f16_sdwa v23, v129 dst_sel:DWORD dst_unused:UNUSED_PAD src0_sel:WORD_1
	v_cvt_f32_f16_e32 v24, v134
	v_cvt_f32_f16_sdwa v25, v134 dst_sel:DWORD dst_unused:UNUSED_PAD src0_sel:WORD_1
	v_permlane32_swap_b32_e32 v128, v132
	v_cvt_f32_f16_sdwa v7, v113 dst_sel:DWORD dst_unused:UNUSED_PAD src0_sel:WORD_1
	v_cvt_f32_f16_e32 v6, v113
	v_cvt_f32_f16_sdwa v9, v110 dst_sel:DWORD dst_unused:UNUSED_PAD src0_sel:WORD_1
	v_cvt_f32_f16_e32 v8, v110
	v_cvt_f32_f16_e32 v26, v128
	v_cvt_f32_f16_sdwa v27, v128 dst_sel:DWORD dst_unused:UNUSED_PAD src0_sel:WORD_1
	v_cvt_f32_f16_e32 v76, v132
	v_cvt_f32_f16_sdwa v77, v132 dst_sel:DWORD dst_unused:UNUSED_PAD src0_sel:WORD_1
	v_pk_add_f32 v[14:15], v[14:15], v[16:17]
	v_pk_add_f32 v[16:17], v[18:19], v[20:21]
	v_pk_add_f32 v[18:19], v[22:23], v[24:25]
	v_pk_mul_f32 v[16:17], v[16:17], s[16:17] op_sel_hi:[1,0]
	v_pk_mul_f32 v[18:19], v[18:19], s[16:17] op_sel_hi:[1,0]
	v_permlane32_swap_b32_e32 v125, v126
	v_cvt_f32_f16_sdwa v11, v111 dst_sel:DWORD dst_unused:UNUSED_PAD src0_sel:WORD_1
	v_cvt_f32_f16_e32 v10, v111
	v_pk_mul_f32 v[16:17], v[70:71], v[16:17]
	v_pk_mul_f32 v[18:19], v[72:73], v[18:19]
	v_pk_add_f32 v[20:21], v[26:27], v[76:77]
	v_pk_fma_f32 v[6:7], v[6:7], s[18:19], v[16:17] op_sel_hi:[1,0,1]
	v_pk_fma_f32 v[8:9], v[8:9], s[18:19], v[18:19] op_sel_hi:[1,0,1]
	v_cvt_f32_f16_e32 v16, v125
	v_cvt_f32_f16_sdwa v17, v125 dst_sel:DWORD dst_unused:UNUSED_PAD src0_sel:WORD_1
	v_cvt_f32_f16_e32 v18, v126
	v_cvt_f32_f16_sdwa v19, v126 dst_sel:DWORD dst_unused:UNUSED_PAD src0_sel:WORD_1
	v_pk_mul_f32 v[20:21], v[20:21], s[16:17] op_sel_hi:[1,0]
	v_permlane32_swap_b32_e32 v127, v130
	v_pk_mul_f32 v[20:21], v[74:75], v[20:21]
	v_cvt_f32_f16_sdwa v5, v112 dst_sel:DWORD dst_unused:UNUSED_PAD src0_sel:WORD_1
	v_cvt_f32_f16_e32 v4, v112
	v_cvt_f32_f16_e32 v78, v127
	v_cvt_f32_f16_sdwa v79, v127 dst_sel:DWORD dst_unused:UNUSED_PAD src0_sel:WORD_1
	v_cvt_f32_f16_e32 v80, v130
	v_cvt_f32_f16_sdwa v81, v130 dst_sel:DWORD dst_unused:UNUSED_PAD src0_sel:WORD_1
	v_pk_fma_f32 v[10:11], v[10:11], s[18:19], v[20:21] op_sel_hi:[1,0,1]
	v_cvt_f32_f16_sdwa v21, v109 dst_sel:DWORD dst_unused:UNUSED_PAD src0_sel:WORD_1
	v_cvt_f32_f16_e32 v20, v109
	v_pk_add_f32 v[16:17], v[16:17], v[18:19]
	v_pk_mul_f32 v[14:15], v[14:15], s[16:17] op_sel_hi:[1,0]
	v_pk_mul_f32 v[16:17], v[16:17], s[16:17] op_sel_hi:[1,0]
	v_permlane32_swap_b32_e32 v123, v124
	v_lshlrev_b64 v[2:3], 12, v[94:95]
	v_cvt_f32_f16_sdwa v13, v108 dst_sel:DWORD dst_unused:UNUSED_PAD src0_sel:WORD_1
	v_cvt_f32_f16_e32 v12, v108
	v_pk_mul_f32 v[14:15], v[68:69], v[14:15]
	v_pk_mul_f32 v[16:17], v[66:67], v[16:17]
	v_lshl_add_u64 v[0:1], v[114:115], 2, s[8:9]
	v_lshl_add_u64 v[2:3], s[6:7], 0, v[2:3]
	v_pk_add_f32 v[22:23], v[78:79], v[80:81]
	v_pk_fma_f32 v[4:5], v[4:5], s[18:19], v[14:15] op_sel_hi:[1,0,1]
	v_pk_fma_f32 v[16:17], v[20:21], s[18:19], v[16:17] op_sel_hi:[1,0,1]
	v_cvt_f32_f16_e32 v18, v123
	v_cvt_f32_f16_sdwa v19, v123 dst_sel:DWORD dst_unused:UNUSED_PAD src0_sel:WORD_1
	v_cvt_f32_f16_e32 v20, v124
	v_cvt_f32_f16_sdwa v21, v124 dst_sel:DWORD dst_unused:UNUSED_PAD src0_sel:WORD_1
	v_cndmask_b32_e64 v1, v3, v1, s[0:1]
	v_pk_mul_f32 v[22:23], v[22:23], s[16:17] op_sel_hi:[1,0]
	v_add_f32_e32 v3, 0, v4
	v_pk_mul_f32 v[22:23], v[64:65], v[22:23]
	v_add_f32_e32 v3, v5, v3
	v_pk_fma_f32 v[12:13], v[12:13], s[18:19], v[22:23] op_sel_hi:[1,0,1]
	v_add_f32_e32 v3, v6, v3
	v_cvt_f32_f16_sdwa v23, v106 dst_sel:DWORD dst_unused:UNUSED_PAD src0_sel:WORD_1
	v_cvt_f32_f16_e32 v22, v106
	v_add_f32_e32 v3, v7, v3
	v_pk_add_f32 v[18:19], v[18:19], v[20:21]
	v_add_f32_e32 v3, v8, v3
	v_pk_mul_f32 v[18:19], v[18:19], s[16:17] op_sel_hi:[1,0]
	v_permlane32_swap_b32_e32 v121, v122
	v_add_f32_e32 v3, v9, v3
	v_pk_mul_f32 v[18:19], v[60:61], v[18:19]
	v_add_f32_e32 v3, v10, v3
	v_pk_fma_f32 v[18:19], v[22:23], s[18:19], v[18:19] op_sel_hi:[1,0,1]
	v_cvt_f32_f16_e32 v20, v121
	v_cvt_f32_f16_sdwa v21, v121 dst_sel:DWORD dst_unused:UNUSED_PAD src0_sel:WORD_1
	v_cvt_f32_f16_e32 v22, v122
	v_cvt_f32_f16_sdwa v23, v122 dst_sel:DWORD dst_unused:UNUSED_PAD src0_sel:WORD_1
	v_add_f32_e32 v3, v11, v3
	v_add_f32_e32 v3, v12, v3
	v_add_f32_e32 v3, v13, v3
	v_cvt_f32_f16_sdwa v25, v107 dst_sel:DWORD dst_unused:UNUSED_PAD src0_sel:WORD_1
	v_cvt_f32_f16_e32 v24, v107
	v_add_f32_e32 v3, v16, v3
	v_pk_add_f32 v[20:21], v[20:21], v[22:23]
	v_add_f32_e32 v3, v17, v3
	v_pk_mul_f32 v[20:21], v[20:21], s[16:17] op_sel_hi:[1,0]
	v_add_f32_e32 v3, v18, v3
	v_pk_mul_f32 v[20:21], v[62:63], v[20:21]
	v_add_f32_e32 v3, v19, v3
	v_pk_fma_f32 v[20:21], v[24:25], s[18:19], v[20:21] op_sel_hi:[1,0,1]
	s_waitcnt vmcnt(0)
	v_cmp_neq_f32_e32 vcc, 0, v82
	v_add_f32_e32 v3, v20, v3
	v_add_f32_e32 v3, v21, v3
	v_mov_b32_e32 v15, v3
	s_nop 1
	v_permlane32_swap_b32_e32 v3, v15
	v_add_f32_e32 v3, v3, v15
	v_mov_b32_e32 v15, v3
	s_nop 1
	v_permlane16_swap_b32_e32 v3, v15
	v_add_f32_e32 v3, v3, v15
	v_cndmask_b32_e32 v14, 0, v120, vcc
	v_cndmask_b32_e64 v0, v2, v0, s[0:1]
	v_add_f32_dpp v3, v3, v3 row_ror:8 row_mask:0xf bank_mask:0xf bound_ctrl:1
	v_mov_b32_e32 v101, v95
	s_nop 0
	v_add_f32_dpp v3, v3, v3 row_ror:4 row_mask:0xf bank_mask:0xf bound_ctrl:1
	s_nop 1
	v_add_f32_dpp v3, v3, v3 quad_perm:[2,3,0,1] row_mask:0xf bank_mask:0xf bound_ctrl:1
	s_nop 1
	v_add_f32_dpp v3, v3, v3 quad_perm:[1,0,3,2] row_mask:0xf bank_mask:0xf bound_ctrl:1
	v_mul_f32_e32 v22, 0x3a800000, v3
	v_pk_add_f32 v[4:5], v[4:5], v[22:23] op_sel_hi:[1,0] neg_lo:[0,1] neg_hi:[0,1]
	v_pk_add_f32 v[6:7], v[6:7], v[22:23] op_sel_hi:[1,0] neg_lo:[0,1] neg_hi:[0,1]
	v_mul_f32_e32 v24, v5, v5
	v_pk_fma_f32 v[24:25], v[4:5], v[4:5], v[24:25] op_sel_hi:[1,1,0]
	v_mul_f32_e32 v26, v7, v7
	v_pk_fma_f32 v[24:25], v[6:7], v[6:7], v[24:25]
	v_pk_add_f32 v[8:9], v[8:9], v[22:23] op_sel_hi:[1,0] neg_lo:[0,1] neg_hi:[0,1]
	v_pk_add_f32 v[24:25], v[26:27], v[24:25] op_sel_hi:[0,1]
	v_pk_fma_f32 v[24:25], v[8:9], v[8:9], v[24:25]
	v_mul_f32_e32 v26, v9, v9
	v_pk_add_f32 v[24:25], v[26:27], v[24:25] op_sel_hi:[0,1]
	v_pk_add_f32 v[10:11], v[10:11], v[22:23] op_sel_hi:[1,0] neg_lo:[0,1] neg_hi:[0,1]
	v_pk_add_f32 v[12:13], v[12:13], v[22:23] op_sel_hi:[1,0] neg_lo:[0,1] neg_hi:[0,1]
	v_pk_fma_f32 v[24:25], v[10:11], v[10:11], v[24:25]
	v_mul_f32_e32 v26, v11, v11
	v_pk_add_f32 v[24:25], v[26:27], v[24:25] op_sel_hi:[0,1]
	v_pk_fma_f32 v[24:25], v[12:13], v[12:13], v[24:25]
	v_mul_f32_e32 v26, v13, v13
	v_pk_add_f32 v[24:25], v[26:27], v[24:25] op_sel_hi:[0,1]
	v_pk_add_f32 v[16:17], v[16:17], v[22:23] op_sel_hi:[1,0] neg_lo:[0,1] neg_hi:[0,1]
	v_pk_add_f32 v[18:19], v[18:19], v[22:23] op_sel_hi:[1,0] neg_lo:[0,1] neg_hi:[0,1]
	v_pk_fma_f32 v[24:25], v[16:17], v[16:17], v[24:25]
	v_mul_f32_e32 v26, v17, v17
	v_pk_add_f32 v[24:25], v[26:27], v[24:25] op_sel_hi:[0,1]
	v_pk_fma_f32 v[24:25], v[18:19], v[18:19], v[24:25]
	v_mul_f32_e32 v26, v19, v19
	v_pk_add_f32 v[24:25], v[26:27], v[24:25] op_sel_hi:[0,1]
	v_pk_add_f32 v[20:21], v[20:21], v[22:23] op_sel_hi:[1,0] neg_lo:[0,1] neg_hi:[0,1]
	s_nop 0
	v_pk_fma_f32 v[22:23], v[20:21], v[20:21], v[24:25]
	v_mul_f32_e32 v24, v21, v21
	v_pk_add_f32 v[22:23], v[24:25], v[22:23] op_sel_hi:[0,1]
	v_mov_b32_e32 v3, v22
	s_nop 1
	v_permlane32_swap_b32_e32 v22, v3
	v_add_f32_e32 v3, v22, v3
	v_mov_b32_e32 v15, v3
	s_nop 1
	v_permlane16_swap_b32_e32 v3, v15
	v_add_f32_e32 v3, v3, v15
	v_lshl_add_u64 v[22:23], v[0:1], 0, v[100:101]
	s_nop 0
	v_add_f32_dpp v3, v3, v3 row_ror:8 row_mask:0xf bank_mask:0xf bound_ctrl:1
	s_nop 1
	v_add_f32_dpp v3, v3, v3 row_ror:4 row_mask:0xf bank_mask:0xf bound_ctrl:1
	s_nop 1
	v_add_f32_dpp v3, v3, v3 quad_perm:[2,3,0,1] row_mask:0xf bank_mask:0xf bound_ctrl:1
	s_nop 1
	v_add_f32_dpp v3, v3, v3 quad_perm:[1,0,3,2] row_mask:0xf bank_mask:0xf bound_ctrl:1
	v_fmamk_f32 v3, v3, 0x3a800000, v119
	v_mul_f32_e32 v15, 0x4b800000, v3
	v_cmp_gt_f32_e32 vcc, s23, v3
	s_nop 1
	v_cndmask_b32_e32 v3, v3, v15, vcc
	v_rsq_f32_e32 v3, v3
	s_nop 0
	v_mul_f32_e32 v0, 0x45800000, v3
	v_cndmask_b32_e32 v24, v3, v0, vcc
	v_pk_mul_f32 v[0:1], v[6:7], v[24:25] op_sel_hi:[1,0]
	v_pk_mul_f32 v[2:3], v[4:5], v[24:25] op_sel_hi:[1,0]
	v_pk_fma_f32 v[0:1], v[58:59], v[0:1], v[54:55]
	v_pk_fma_f32 v[4:5], v[56:57], v[2:3], v[52:53]
	v_pk_add_f32 v[2:3], v[14:15], v[0:1] op_sel_hi:[0,1]
	v_pk_add_f32 v[0:1], v[14:15], v[4:5] op_sel_hi:[0,1]
	global_store_dwordx4 v[22:23], v[0:3], off
	s_nop 1
	v_pk_mul_f32 v[0:1], v[10:11], v[24:25] op_sel_hi:[1,0]
	v_pk_mul_f32 v[2:3], v[8:9], v[24:25] op_sel_hi:[1,0]
	v_pk_fma_f32 v[0:1], v[50:51], v[0:1], v[46:47]
	v_pk_fma_f32 v[4:5], v[48:49], v[2:3], v[44:45]
	v_pk_add_f32 v[2:3], v[14:15], v[0:1] op_sel_hi:[0,1]
	v_pk_add_f32 v[0:1], v[14:15], v[4:5] op_sel_hi:[0,1]
	global_store_dwordx4 v[22:23], v[0:3], off offset:512
	s_nop 1
	v_pk_mul_f32 v[0:1], v[16:17], v[24:25] op_sel_hi:[1,0]
	v_pk_mul_f32 v[2:3], v[12:13], v[24:25] op_sel_hi:[1,0]
	v_pk_fma_f32 v[0:1], v[42:43], v[0:1], v[38:39]
	v_pk_fma_f32 v[4:5], v[40:41], v[2:3], v[36:37]
	v_pk_add_f32 v[2:3], v[14:15], v[0:1] op_sel_hi:[0,1]
	v_pk_add_f32 v[0:1], v[14:15], v[4:5] op_sel_hi:[0,1]
	global_store_dwordx4 v[22:23], v[0:3], off offset:1024
	s_nop 1
	v_pk_mul_f32 v[0:1], v[20:21], v[24:25] op_sel_hi:[1,0]
	v_pk_mul_f32 v[2:3], v[18:19], v[24:25] op_sel_hi:[1,0]
	v_pk_fma_f32 v[0:1], v[34:35], v[0:1], v[30:31]
	v_pk_fma_f32 v[4:5], v[32:33], v[2:3], v[28:29]
	v_pk_add_f32 v[2:3], v[14:15], v[0:1] op_sel_hi:[0,1]
	v_pk_add_f32 v[0:1], v[14:15], v[4:5] op_sel_hi:[0,1]
	global_store_dwordx4 v[22:23], v[0:3], off offset:1536
	s_branch .Lg2_next
.Lg2_save:
	ds_write2st64_b32 v227, v121, v122 offset0:0 offset1:1
	ds_write2st64_b32 v227, v123, v124 offset0:2 offset1:3
	ds_write2st64_b32 v227, v125, v126 offset0:4 offset1:5
	ds_write2st64_b32 v227, v127, v128 offset0:6 offset1:7
	ds_write2st64_b32 v227, v129, v130 offset0:8 offset1:9
	ds_write2st64_b32 v227, v131, v132 offset0:10 offset1:11
	ds_write2st64_b32 v227, v133, v134 offset0:12 offset1:13
	ds_write2st64_b32 v227, v135, v136 offset0:14 offset1:15
.Lg2_next:
	s_add_u32 s42, s42, 1
	s_add_u32 s45, s45, s33
	s_cmp_lt_u32 s42, 4
	s_cbranch_scc1 .Lg2_tok
.Lg2_sweep_done:
	s_add_u32 s43, s43, 1
	s_cmp_lt_u32 s43, 2
	s_cbranch_scc1 .Lg2_sweep
	s_lshl_b32 s46, s33, 2
	s_add_u32 s41, s41, s46
	s_xor_b32 s44, s44, 1
	s_cmp_lt_u32 s41, s17
	s_cbranch_scc1 .Lg2_group
